# item loop BB0_800: issue the 4 serialized bf16 dwordx2 loads together with counted vmcnt waits, on top of v47
# baseline (speedup 1.0000x reference)
; __device__ __forceinline__ float bflo(unsigned w) { return __uint_as_float(w << 16); }
; __device__ __forceinline__ float bfhi(unsigned w) { return __uint_as_float(w & 0xffff0000u); }
; __device__ void fold_rows(const Params& p, int nslice, const float* ssq, float* rsv) {
;     ...
;     for (int idx = p.bid * 8 + wave; idx < 256; idx += p.nblk * 8) {
;         const int row = MP - 256 + idx; bf16_t* hp = hb + (size_t)row * DM; f32x4 v[4]; float ss = 0.f;
; #pragma unroll
;         for (int i = 0; i < 4; ++i) { const u32x2 w = *(const u32x2*)(hp + lane * 4 + 256 * i); v[i] = (f32x4){bflo(w.x), bfhi(w.x), bflo(w.y), bfhi(w.y)}; }
;         const float* pt = (const float*)(p.ws + WS_PART) + (size_t)idx * DM + lane * 4;
;         for (int s0 = 0; s0 < nslice; s0 += 4) {
;             f32x4 tq[4][4];
; #pragma unroll
;             for (int q = 0; q < 4; ++q) { const int sl = s0 + q < nslice ? s0 + q : nslice - 1;
; #pragma unroll
;                 for (int i = 0; i < 4; ++i) tq[q][i] = *(const f32x4*)(pt + (size_t)sl * 256 * DM + 256 * i); }
; #pragma unroll
;             for (int q = 0; q < 4; ++q) { const float on = s0 + q < nslice ? 1.f : 0.f;
; #pragma unroll
;                 for (int i = 0; i < 4; ++i) v[i] += tq[q][i] * on; } }
.LBB0_800:
	v_lshl_add_u64 v[52:53], s[36:37], 0, v[48:49]
	s_waitcnt lgkmcnt(0)
	global_load_dwordx2 v[2:3], v[52:53], off
	global_load_dwordx2 v[100:101], v[52:53], off offset:512
	global_load_dwordx2 v[102:103], v[52:53], off offset:1024
	global_load_dwordx2 v[104:105], v[52:53], off offset:1536
	v_lshl_add_u64 v[54:55], s[36:37], 0, v[46:47]
	s_mov_b32 s20, 0x1d978000
	v_add_co_u32_e64 v14, s[40:41], s20, v54
	s_mov_b32 s20, 0x1da78000
	s_nop 0
	v_addc_co_u32_e64 v15, s[40:41], 0, v55, s[40:41]
	v_add_co_u32_e64 v30, s[40:41], s20, v54
	s_mov_b32 s20, 0x1db78000
	s_nop 0
	v_addc_co_u32_e64 v31, s[40:41], 0, v55, s[40:41]
	v_add_co_u32_e64 v56, s[40:41], s20, v54
	s_mov_b32 s20, 0x1dc78000
	s_nop 0
	v_addc_co_u32_e64 v57, s[40:41], 0, v55, s[40:41]
	v_add_co_u32_e64 v80, s[40:41], s20, v54
	s_mov_b32 s20, 0x1dd78000
	s_nop 0
	v_addc_co_u32_e64 v81, s[40:41], 0, v55, s[40:41]
	s_waitcnt vmcnt(3)
	v_lshlrev_b32_e32 v84, 16, v2
	v_and_b32_e32 v85, 0xffff0000, v2
	v_lshlrev_b32_e32 v86, 16, v3
	v_and_b32_e32 v87, 0xffff0000, v3
	s_waitcnt vmcnt(2)
	s_nop 0
	v_lshlrev_b32_e32 v88, 16, v100
	v_and_b32_e32 v89, 0xffff0000, v100
	v_lshlrev_b32_e32 v90, 16, v101
	v_and_b32_e32 v91, 0xffff0000, v101
	s_waitcnt vmcnt(1)
	s_nop 0
	v_lshlrev_b32_e32 v92, 16, v102
	v_and_b32_e32 v93, 0xffff0000, v102
	v_lshlrev_b32_e32 v94, 16, v103
	v_and_b32_e32 v95, 0xffff0000, v103
	s_waitcnt vmcnt(0)
	s_nop 0
	v_lshlrev_b32_e32 v96, 16, v104
	v_and_b32_e32 v97, 0xffff0000, v104
	v_lshlrev_b32_e32 v98, 16, v105
	v_and_b32_e32 v99, 0xffff0000, v105
	global_load_dwordx4 v[2:5], v[14:15], off
	global_load_dwordx4 v[6:9], v[14:15], off offset:1024
	global_load_dwordx4 v[10:13], v[14:15], off offset:2048
	s_nop 0
	global_load_dwordx4 v[14:17], v[14:15], off offset:3072
	s_nop 0
	global_load_dwordx4 v[18:21], v[30:31], off
	global_load_dwordx4 v[22:25], v[30:31], off offset:1024
	global_load_dwordx4 v[26:29], v[30:31], off offset:2048
	s_nop 0
	global_load_dwordx4 v[30:33], v[30:31], off offset:3072
	s_nop 0
	global_load_dwordx4 v[34:37], v[56:57], off
	global_load_dwordx4 v[38:41], v[56:57], off offset:1024
	global_load_dwordx4 v[42:45], v[56:57], off offset:2048
	s_nop 0
	global_load_dwordx4 v[56:59], v[56:57], off offset:3072
	s_nop 0
	global_load_dwordx4 v[60:63], v[80:81], off
	global_load_dwordx4 v[64:67], v[80:81], off offset:1024
	global_load_dwordx4 v[68:71], v[80:81], off offset:2048
	s_nop 0
	global_load_dwordx4 v[80:83], v[80:81], off offset:3072
	s_waitcnt vmcnt(15)
	v_pk_add_f32 v[2:3], v[2:3], v[84:85]
	v_pk_add_f32 v[4:5], v[4:5], v[86:87]
	s_waitcnt vmcnt(11)
	v_pk_add_f32 v[2:3], v[2:3], v[18:19]
	v_pk_add_f32 v[4:5], v[4:5], v[20:21]
	s_waitcnt vmcnt(7)
	v_pk_add_f32 v[2:3], v[2:3], v[34:35]
	v_pk_add_f32 v[4:5], v[4:5], v[36:37]
	s_waitcnt vmcnt(3)
	v_pk_add_f32 v[36:37], v[2:3], v[60:61]
	v_add_co_u32_e64 v2, s[40:41], s20, v54
	v_pk_add_f32 v[14:15], v[14:15], v[96:97]
	s_nop 0
	v_addc_co_u32_e64 v3, s[40:41], 0, v55, s[40:41]
	s_mov_b32 s20, 0x1de78000
	v_pk_add_f32 v[6:7], v[6:7], v[88:89]
	v_pk_add_f32 v[8:9], v[8:9], v[90:91]
	v_pk_add_f32 v[10:11], v[10:11], v[92:93]
	v_pk_add_f32 v[12:13], v[12:13], v[94:95]
	v_pk_add_f32 v[16:17], v[16:17], v[98:99]
	v_pk_add_f32 v[14:15], v[14:15], v[30:31]
	v_add_co_u32_e64 v18, s[40:41], s20, v54
	v_pk_add_f32 v[8:9], v[8:9], v[24:25]
	v_pk_add_f32 v[6:7], v[6:7], v[22:23]
	v_pk_add_f32 v[12:13], v[12:13], v[28:29]
	v_pk_add_f32 v[10:11], v[10:11], v[26:27]
	v_pk_add_f32 v[16:17], v[16:17], v[32:33]
	v_pk_add_f32 v[14:15], v[14:15], v[56:57]
	v_addc_co_u32_e64 v19, s[40:41], 0, v55, s[40:41]
	s_mov_b32 s20, 0x1df78000
	v_pk_add_f32 v[8:9], v[8:9], v[40:41]
	v_pk_add_f32 v[6:7], v[6:7], v[38:39]
	v_pk_add_f32 v[12:13], v[12:13], v[44:45]
	v_pk_add_f32 v[10:11], v[10:11], v[42:43]
	v_pk_add_f32 v[16:17], v[16:17], v[58:59]
	s_waitcnt vmcnt(0)
	v_pk_add_f32 v[58:59], v[14:15], v[80:81]
	v_add_co_u32_e64 v80, s[40:41], s20, v54
	v_pk_add_f32 v[34:35], v[4:5], v[62:63]
	v_pk_add_f32 v[38:39], v[8:9], v[66:67]
	v_pk_add_f32 v[40:41], v[6:7], v[64:65]
	v_pk_add_f32 v[42:43], v[12:13], v[70:71]
	v_pk_add_f32 v[44:45], v[10:11], v[68:69]
	v_pk_add_f32 v[56:57], v[16:17], v[82:83]
	global_load_dwordx4 v[14:17], v[2:3], off
	global_load_dwordx4 v[10:13], v[2:3], off offset:1024
	global_load_dwordx4 v[6:9], v[2:3], off offset:2048
	s_nop 0
	global_load_dwordx4 v[2:5], v[2:3], off offset:3072
	v_addc_co_u32_e64 v81, s[40:41], 0, v55, s[40:41]
	s_mov_b32 s20, 0x1e078000
	global_load_dwordx4 v[30:33], v[18:19], off
	global_load_dwordx4 v[26:29], v[18:19], off offset:1024
	global_load_dwordx4 v[22:25], v[18:19], off offset:2048
	s_nop 0
	global_load_dwordx4 v[18:21], v[18:19], off offset:3072
	v_add_co_u32_e64 v96, s[40:41], s20, v54
	global_load_dwordx4 v[60:63], v[80:81], off
	global_load_dwordx4 v[64:67], v[80:81], off offset:1024
	global_load_dwordx4 v[68:71], v[80:81], off offset:2048
	s_nop 0
	global_load_dwordx4 v[80:83], v[80:81], off offset:3072
	v_addc_co_u32_e64 v97, s[40:41], 0, v55, s[40:41]
	global_load_dwordx4 v[84:87], v[96:97], off
	global_load_dwordx4 v[88:91], v[96:97], off offset:1024
	global_load_dwordx4 v[92:95], v[96:97], off offset:2048
	s_nop 0
	global_load_dwordx4 v[96:99], v[96:97], off offset:3072
	s_mov_b32 s20, 0x1e178000
	s_waitcnt vmcnt(15)
	v_pk_add_f32 v[16:17], v[34:35], v[16:17]
	v_pk_add_f32 v[14:15], v[36:37], v[14:15]
	s_waitcnt vmcnt(14)
	v_pk_add_f32 v[12:13], v[38:39], v[12:13]
	s_waitcnt vmcnt(12)
	v_pk_add_f32 v[2:3], v[58:59], v[2:3]
	v_pk_add_f32 v[4:5], v[56:57], v[4:5]
	v_pk_add_f32 v[10:11], v[40:41], v[10:11]
	v_pk_add_f32 v[8:9], v[42:43], v[8:9]
	s_waitcnt vmcnt(8)
; __device__ __forceinline__ unsigned cvt_pk_bf16(float lo, float hi) { const f32x2 f = {lo, hi}; const bf16n2 v = __builtin_convertvector(f, bf16n2); return __builtin_bit_cast(unsigned, v); }
; __device__ void fold_rows(const Params& p, int nslice, const float* ssq, float* rsv) {
;     ...
;             for (int q = 0; q < 4; ++q) { const int sl = s0 + q < nslice ? s0 + q : nslice - 1;
; #pragma unroll
;                 for (int i = 0; i < 4; ++i) tq[q][i] = *(const f32x4*)(pt + (size_t)sl * 256 * DM + 256 * i); }
; #pragma unroll
;             for (int q = 0; q < 4; ++q) { const float on = s0 + q < nslice ? 1.f : 0.f;
; #pragma unroll
;                 for (int i = 0; i < 4; ++i) v[i] += tq[q][i] * on; } }
; #pragma unroll
;         for (int i = 0; i < 4; ++i) { u32x2 w; w.x = cvt_pk_bf16(v[i][0], v[i][1]); w.y = cvt_pk_bf16(v[i][2], v[i][3]); *(u32x2*)(hp + lane * 4 + 256 * i) = w;
;             ss += v[i][0] * v[i][0] + v[i][1] * v[i][1] + v[i][2] * v[i][2] + v[i][3] * v[i][3]; }
;         ss = wave_sum(ss, lane);
;         if (lane == 0) rsv[row] = rsqrtf(ss * (1.0f / DM) + EPS);
	v_pk_add_f32 v[2:3], v[2:3], v[18:19]
	v_pk_add_f32 v[4:5], v[4:5], v[20:21]
	v_pk_add_f32 v[6:7], v[44:45], v[6:7]
	s_waitcnt vmcnt(4)
	v_pk_add_f32 v[2:3], v[2:3], v[80:81]
	v_pk_add_f32 v[16:17], v[16:17], v[32:33]
	v_pk_add_f32 v[14:15], v[14:15], v[30:31]
	s_waitcnt vmcnt(0)
	v_pk_add_f32 v[58:59], v[2:3], v[96:97]
	v_add_co_u32_e64 v2, s[40:41], s20, v54
	s_mov_b32 s20, 0x1e278000
	s_nop 0
	v_addc_co_u32_e64 v3, s[40:41], 0, v55, s[40:41]
	v_pk_add_f32 v[4:5], v[4:5], v[82:83]
	global_load_dwordx4 v[80:83], v[2:3], off
	global_load_dwordx4 v[42:45], v[2:3], off offset:1024
	global_load_dwordx4 v[38:41], v[2:3], off offset:2048
	global_load_dwordx4 v[30:33], v[2:3], off offset:3072
	v_add_co_u32_e64 v2, s[40:41], s20, v54
	v_pk_add_f32 v[8:9], v[8:9], v[24:25]
	v_pk_add_f32 v[14:15], v[14:15], v[60:61]
	v_addc_co_u32_e64 v3, s[40:41], 0, v55, s[40:41]
	s_mov_b32 s20, 0x1e378000
	v_pk_add_f32 v[12:13], v[12:13], v[28:29]
	v_pk_add_f32 v[10:11], v[10:11], v[26:27]
	v_pk_add_f32 v[6:7], v[6:7], v[22:23]
	v_pk_add_f32 v[8:9], v[8:9], v[70:71]
	v_pk_add_f32 v[70:71], v[14:15], v[84:85]
	v_add_co_u32_e64 v14, s[40:41], s20, v54
	v_pk_add_f32 v[16:17], v[16:17], v[62:63]
	v_pk_add_f32 v[12:13], v[12:13], v[66:67]
	v_pk_add_f32 v[10:11], v[10:11], v[64:65]
	v_pk_add_f32 v[6:7], v[6:7], v[68:69]
	global_load_dwordx4 v[34:37], v[2:3], off
	global_load_dwordx4 v[26:29], v[2:3], off offset:1024
	global_load_dwordx4 v[22:25], v[2:3], off offset:2048
	global_load_dwordx4 v[18:21], v[2:3], off offset:3072
	v_addc_co_u32_e64 v15, s[40:41], 0, v55, s[40:41]
	v_pk_add_f32 v[68:69], v[16:17], v[86:87]
	v_pk_add_f32 v[64:65], v[12:13], v[90:91]
	v_pk_add_f32 v[66:67], v[10:11], v[88:89]
	v_pk_add_f32 v[60:61], v[8:9], v[94:95]
	v_pk_add_f32 v[62:63], v[6:7], v[92:93]
	v_pk_add_f32 v[56:57], v[4:5], v[98:99]
	global_load_dwordx4 v[2:5], v[14:15], off
	global_load_dwordx4 v[6:9], v[14:15], off offset:1024
	global_load_dwordx4 v[10:13], v[14:15], off offset:2048
	s_nop 0
	global_load_dwordx4 v[14:17], v[14:15], off offset:3072
	s_waitcnt vmcnt(11)
	v_pk_add_f32 v[54:55], v[68:69], v[82:83]
	v_pk_add_f32 v[68:69], v[70:71], v[80:81]
	s_waitcnt vmcnt(10)
	v_pk_add_f32 v[44:45], v[64:65], v[44:45]
	s_waitcnt vmcnt(8)
	v_pk_add_f32 v[32:33], v[56:57], v[32:33]
	v_pk_add_f32 v[30:31], v[58:59], v[30:31]
	v_pk_add_f32 v[42:43], v[66:67], v[42:43]
	v_pk_add_f32 v[40:41], v[60:61], v[40:41]
	v_pk_add_f32 v[38:39], v[62:63], v[38:39]
	s_waitcnt vmcnt(7)
	v_pk_add_f32 v[36:37], v[54:55], v[36:37]
	v_pk_add_f32 v[34:35], v[68:69], v[34:35]
	s_waitcnt vmcnt(6)
	v_pk_add_f32 v[28:29], v[44:45], v[28:29]
	s_waitcnt vmcnt(4)
	v_pk_add_f32 v[20:21], v[32:33], v[20:21]
	v_pk_add_f32 v[18:19], v[30:31], v[18:19]
	v_pk_add_f32 v[26:27], v[42:43], v[26:27]
	v_pk_add_f32 v[24:25], v[40:41], v[24:25]
	v_pk_add_f32 v[22:23], v[38:39], v[22:23]
	s_waitcnt vmcnt(3)
	v_pk_add_f32 v[30:31], v[36:37], v[4:5]
	v_pk_add_f32 v[32:33], v[34:35], v[2:3]
	v_pk_fma_f32 v[4:5], v[4:5], 0, v[30:31] op_sel_hi:[1,0,1]
	s_waitcnt vmcnt(0)
	v_pk_add_f32 v[18:19], v[18:19], v[14:15]
	v_pk_fma_f32 v[2:3], v[2:3], 0, v[32:33] op_sel_hi:[1,0,1]
	v_pk_add_f32 v[28:29], v[28:29], v[8:9]
	v_pk_add_f32 v[26:27], v[26:27], v[6:7]
	v_pk_fma_f32 v[14:15], v[14:15], 0, v[18:19] op_sel_hi:[1,0,1]
	v_cvt_pk_bf16_f32 v18, v2, v3
	v_cvt_pk_bf16_f32 v19, v4, v5
	v_pk_fma_f32 v[8:9], v[8:9], 0, v[28:29] op_sel_hi:[1,0,1]
	v_pk_fma_f32 v[6:7], v[6:7], 0, v[26:27] op_sel_hi:[1,0,1]
	global_store_dwordx2 v[52:53], v[18:19], off
	v_mul_f32_e32 v18, v3, v3
	v_fmac_f32_e32 v18, v2, v2
	v_cvt_pk_bf16_f32 v2, v6, v7
	v_cvt_pk_bf16_f32 v3, v8, v9
	global_store_dwordx2 v[52:53], v[2:3], off offset:512
	v_mul_f32_e32 v2, v7, v7
	v_fmac_f32_e32 v2, v6, v6
	v_pk_add_f32 v[24:25], v[24:25], v[12:13]
	v_pk_add_f32 v[22:23], v[22:23], v[10:11]
	v_fmac_f32_e32 v18, v4, v4
	v_fmac_f32_e32 v2, v8, v8
	v_pk_fma_f32 v[12:13], v[12:13], 0, v[24:25] op_sel_hi:[1,0,1]
	v_pk_fma_f32 v[10:11], v[10:11], 0, v[22:23] op_sel_hi:[1,0,1]
	v_fmac_f32_e32 v18, v5, v5
	v_fmac_f32_e32 v2, v9, v9
	v_add_f32_e32 v4, v18, v2
	v_cvt_pk_bf16_f32 v2, v10, v11
	v_cvt_pk_bf16_f32 v3, v12, v13
	global_store_dwordx2 v[52:53], v[2:3], off offset:1024
	v_mul_f32_e32 v2, v11, v11
	v_fmac_f32_e32 v2, v10, v10
	v_pk_add_f32 v[20:21], v[20:21], v[16:17]
	v_fmac_f32_e32 v2, v12, v12
	v_pk_fma_f32 v[16:17], v[16:17], 0, v[20:21] op_sel_hi:[1,0,1]
	v_fmac_f32_e32 v2, v13, v13
	v_add_f32_e32 v4, v4, v2
	v_cvt_pk_bf16_f32 v2, v14, v15
	v_cvt_pk_bf16_f32 v3, v16, v17
	global_store_dwordx2 v[52:53], v[2:3], off offset:1536
	v_mul_f32_e32 v2, v15, v15
	v_fmac_f32_e32 v2, v14, v14
	v_fmac_f32_e32 v2, v16, v16
	v_fmac_f32_e32 v2, v17, v17
	v_add_f32_e32 v2, v4, v2
	ds_bpermute_b32 v3, v73, v2
	s_waitcnt lgkmcnt(0)
	v_add_f32_e32 v2, v2, v3
	ds_bpermute_b32 v3, v74, v2
	s_waitcnt lgkmcnt(0)
	v_add_f32_e32 v2, v2, v3
	ds_bpermute_b32 v3, v75, v2
	s_waitcnt lgkmcnt(0)
	v_add_f32_e32 v2, v2, v3
	ds_bpermute_b32 v3, v76, v2
	s_waitcnt lgkmcnt(0)
	v_add_f32_e32 v2, v2, v3
	ds_bpermute_b32 v3, v77, v2
	s_waitcnt lgkmcnt(0)
	v_add_f32_e32 v2, v2, v3
	ds_bpermute_b32 v3, v78, v2
	s_and_saveexec_b64 s[50:51], vcc
	s_cbranch_execz .LBB0_799
	s_waitcnt lgkmcnt(0)
	v_add_f32_e32 v2, v2, v3
	v_fmamk_f32 v2, v2, 0x3a800000, v229
	s_mov_b32 s20, 0x800000
	v_mul_f32_e32 v3, 0x4b800000, v2
	v_cmp_gt_f32_e64 s[40:41], s20, v2
	s_nop 1
	v_cndmask_b32_e64 v2, v2, v3, s[40:41]
	v_rsq_f32_e32 v2, v2
	s_nop 0
	v_mul_f32_e32 v3, 0x45800000, v2
	v_cndmask_b32_e64 v4, v2, v3, s[40:41]
	v_lshl_add_u64 v[2:3], s[36:37], 0, v[50:51]
	global_store_dword v[2:3], v4, off
	s_branch .LBB0_799
